# EpiScale GEMM: epilogue ss loads hoisted, full-line DPP stores (QKV), preheader vmcnt0 removed + relaxed first-iteration waits, saddr LDS-DMA, no setprio flips
# baseline (speedup 1.0000x reference)
; template <class Epi, class Sched, bool ALIGN_EPI = false, bool SP2 = false>
; __device__ __forceinline__ void gemm_phase(PG8_LAS unsigned char* lds, const Gemm g, const Sched& S, const Epi& E) {
;     ...
;         const bool has_next = S.next(ui + 1, nxt);
;         const char* nA = has_next ? (const char*)g.A + (size_t)nxt.pm * tstep : cA; const char* nB = has_next ? (const char*)g.Bt + (size_t)nxt.pn * tstep : cB;
;         for (int t = 0; t < nt; t += 2) {
;             const bool last = (t == nt - 2);
;             const char* a1 = cA + (size_t)(t + 1) * kstep;
;             const char* a2 = last ? nA : cA + (size_t)(t + 2) * kstep; const char* b2 = last ? nB : cB + (size_t)(t + 2) * kstep;
;             const char* a3 = a2 + kstep; const char* b3 = b2 + kstep;
;     ...
; #pragma unroll
;         for (int a = 0; a < 2; ++a)
; #pragma unroll
;             for (int b = 0; b < 2; ++b)
; #pragma unroll
;                 for (int m = 0; m < 4; ++m)
; #pragma unroll
;                     for (int n = 0; n < 2; ++n) acc[a][b][m][n] = (f32x4){0.f, 0.f, 0.f, 0.f};
;         cur = nxt; cA = nA; cB = nB; ++ui;
.LBB0_353:
	s_ashr_i32 s71, s70, 31
	s_lshl_b64 s[72:73], s[70:71], 19
	s_add_u32 s72, s52, s72
	s_addc_u32 s73, s53, s73
	s_and_b64 s[74:75], s[38:39], exec
	s_cselect_b32 s1, s73, s43
	s_cselect_b32 s34, s72, s42
	s_ashr_i32 s69, s68, 31
	s_lshl_b64 s[74:75], s[68:69], 19
	s_add_u32 s74, s44, s74
	s_addc_u32 s75, s45, s75
	s_and_b64 s[88:89], s[38:39], exec
	s_cselect_b32 s41, s75, s77
	s_cselect_b32 s69, s74, s76
	s_add_u32 s42, s42, 0x40080
	s_addc_u32 s43, s43, 0
	s_add_u32 s71, s76, 0x100
	v_mov_b32_e32 v0, 0
	s_addc_u32 s78, s77, 0
	s_mov_b32 s88, -2
	v_mov_b32_e32 v1, v0
	v_mov_b32_e32 v2, v0
	v_mov_b32_e32 v3, v0
	v_mov_b32_e32 v4, v0
	v_mov_b32_e32 v5, v0
	v_mov_b32_e32 v6, v0
	v_mov_b32_e32 v7, v0
	v_mov_b32_e32 v16, v0
	v_mov_b32_e32 v17, v0
	v_mov_b32_e32 v18, v0
	v_mov_b32_e32 v19, v0
	v_mov_b32_e32 v20, v0
	v_mov_b32_e32 v21, v0
	v_mov_b32_e32 v22, v0
	v_mov_b32_e32 v23, v0
	v_mov_b32_e32 v32, v0
	v_mov_b32_e32 v33, v0
	v_mov_b32_e32 v34, v0
	v_mov_b32_e32 v35, v0
	v_mov_b32_e32 v36, v0
	v_mov_b32_e32 v37, v0
	v_mov_b32_e32 v38, v0
	v_mov_b32_e32 v39, v0
	v_mov_b32_e32 v48, v0
	v_mov_b32_e32 v49, v0
	v_mov_b32_e32 v50, v0
	v_mov_b32_e32 v51, v0
	v_mov_b32_e32 v52, v0
	v_mov_b32_e32 v53, v0
	v_mov_b32_e32 v54, v0
	v_mov_b32_e32 v55, v0
	v_mov_b32_e32 v8, v0
	v_mov_b32_e32 v9, v0
	v_mov_b32_e32 v10, v0
	v_mov_b32_e32 v11, v0
	v_mov_b32_e32 v12, v0
	v_mov_b32_e32 v13, v0
	v_mov_b32_e32 v14, v0
	v_mov_b32_e32 v15, v0
	v_mov_b32_e32 v24, v0
	v_mov_b32_e32 v25, v0
	v_mov_b32_e32 v26, v0
	v_mov_b32_e32 v27, v0
	v_mov_b32_e32 v28, v0
	v_mov_b32_e32 v29, v0
	v_mov_b32_e32 v30, v0
	v_mov_b32_e32 v31, v0
	v_mov_b32_e32 v40, v0
	v_mov_b32_e32 v41, v0
	v_mov_b32_e32 v42, v0
	v_mov_b32_e32 v43, v0
	v_mov_b32_e32 v44, v0
	v_mov_b32_e32 v45, v0
	v_mov_b32_e32 v46, v0
	v_mov_b32_e32 v47, v0
	v_mov_b32_e32 v56, v0
	v_mov_b32_e32 v57, v0
	v_mov_b32_e32 v58, v0
	v_mov_b32_e32 v59, v0
	v_mov_b32_e32 v60, v0
	v_mov_b32_e32 v61, v0
	v_mov_b32_e32 v62, v0
	v_mov_b32_e32 v63, v0
	v_mov_b32_e32 v64, v0
	v_mov_b32_e32 v65, v0
	v_mov_b32_e32 v66, v0
	v_mov_b32_e32 v67, v0
	v_mov_b32_e32 v68, v0
	v_mov_b32_e32 v69, v0
	v_mov_b32_e32 v70, v0
	v_mov_b32_e32 v71, v0
	v_mov_b32_e32 v96, v0
	v_mov_b32_e32 v97, v0
	v_mov_b32_e32 v98, v0
	v_mov_b32_e32 v99, v0
	v_mov_b32_e32 v100, v0
	v_mov_b32_e32 v101, v0
	v_mov_b32_e32 v102, v0
	v_mov_b32_e32 v103, v0
	v_mov_b32_e32 v114, v0
	v_mov_b32_e32 v115, v0
	v_mov_b32_e32 v116, v0
	v_mov_b32_e32 v117, v0
	v_mov_b32_e32 v118, v0
	v_mov_b32_e32 v119, v0
	v_mov_b32_e32 v120, v0
	v_mov_b32_e32 v121, v0
	v_mov_b32_e32 v130, v0
	v_mov_b32_e32 v131, v0
	v_mov_b32_e32 v132, v0
	v_mov_b32_e32 v133, v0
	v_mov_b32_e32 v134, v0
	v_mov_b32_e32 v135, v0
	v_mov_b32_e32 v136, v0
	v_mov_b32_e32 v137, v0
	v_mov_b32_e32 v72, v0
	v_mov_b32_e32 v73, v0
	v_mov_b32_e32 v74, v0
	v_mov_b32_e32 v75, v0
	v_mov_b32_e32 v76, v0
	v_mov_b32_e32 v77, v0
	v_mov_b32_e32 v78, v0
	v_mov_b32_e32 v79, v0
	v_mov_b32_e32 v104, v0
	v_mov_b32_e32 v105, v0
	v_mov_b32_e32 v106, v0
	v_mov_b32_e32 v107, v0
	v_mov_b32_e32 v108, v0
	v_mov_b32_e32 v109, v0
	v_mov_b32_e32 v110, v0
	v_mov_b32_e32 v111, v0
	v_mov_b32_e32 v122, v0
	v_mov_b32_e32 v123, v0
	v_mov_b32_e32 v124, v0
	v_mov_b32_e32 v125, v0
	v_mov_b32_e32 v126, v0
	v_mov_b32_e32 v127, v0
	v_mov_b32_e32 v128, v0
	v_mov_b32_e32 v129, v0
	v_mov_b32_e32 v138, v0
	v_mov_b32_e32 v139, v0
	v_mov_b32_e32 v140, v0
	v_mov_b32_e32 v141, v0
	v_mov_b32_e32 v142, v0
	v_mov_b32_e32 v143, v0
	v_mov_b32_e32 v144, v0
	v_mov_b32_e32 v145, v0
; #define PG8_STAGE(bufoff, gbase, voff) do { _Pragma("unroll") for (int _i = 0; _i < 2; ++_i) \
;         __builtin_amdgcn_global_load_lds((const unsigned*)((const char*)(gbase) + (voff)[_i]), (PG8_LAS unsigned*)(lds + (bufoff) + ldsw + _i * 8192), 16, 0, 0); } while (0)
; #define PG8_LDA(dst, b, h) do { _Pragma("unroll") for (int m = 0; m < 4; ++m) _Pragma("unroll") for (int k = 0; k < 2; ++k) dst[m][k] = *(const PG8_LAS bf16x8*)(lds + PG8_SA(b, h) + aoff + m * 2048 + k * 1024); } while (0)
; #define PG8_LDB(dst, b, h) do { _Pragma("unroll") for (int n = 0; n < 2; ++n) _Pragma("unroll") for (int k = 0; k < 2; ++k) dst[n][k] = *(const PG8_LAS bf16x8*)(lds + PG8_SB(b, h) + boff + n * 2048 + k * 1024); } while (0)
; #define PG8_MMA(ai, bj, At, Bt) do { __builtin_amdgcn_s_setprio(1); _Pragma("unroll") for (int m = 0; m < 4; ++m) _Pragma("unroll") for (int n = 0; n < 2; ++n) _Pragma("unroll") for (int k = 0; k < 2; ++k) \
;         acc[ai][bj][m][n] = __builtin_amdgcn_mfma_f32_16x16x32_bf16(Bt[n][k], At[m][k], acc[ai][bj][m][n], 0, 0, 0); __builtin_amdgcn_s_setprio(0); } while (0)
; #define PG8_WAIT_V(n) asm volatile("s_waitcnt vmcnt(" #n ")" ::: "memory")
; #define PG8_WAIT_L(n) asm volatile("s_waitcnt lgkmcnt(" #n ")" ::: "memory")
; template <class Epi, class Sched, bool ALIGN_EPI = false, bool SP2 = false>
; __device__ __forceinline__ void gemm_phase(PG8_LAS unsigned char* lds, const Gemm g, const Sched& S, const Epi& E) {
;     ...
;             const bool last = (t == nt - 2);
;             const char* a1 = cA + (size_t)(t + 1) * kstep;
;             const char* a2 = last ? nA : cA + (size_t)(t + 2) * kstep; const char* b2 = last ? nB : cB + (size_t)(t + 2) * kstep;
;             const char* a3 = a2 + kstep; const char* b3 = b2 + kstep;
;             if (last && has_next) S.a_ready(nxt);
;             if constexpr (SP2) {
;             PG8_LDB(B0, 0, 0); PG8_LDB(B1, 0, 1); PG8_SCHED; PG8_LDA(At, 0, 0); PG8_STAGE(PG8_SA(1, 1), a1 + hstep, voffA);
;             PG8_WAIT_V(8); PG8_WAIT_L(0); PG8_BAR; PG8_MMA(0, 0, At, B0); PG8_MMA(0, 1, At, B1); PG8_BAR; PG8_SCHED;
;             PG8_LDA(At, 0, 1); PG8_STAGE(PG8_SB(0, 0), b2, voffB); PG8_STAGE(PG8_SB(0, 1), b2 + hstep, voffB); PG8_STAGE(PG8_SA(0, 0), a2, voffA);
;             PG8_WAIT_V(8); PG8_WAIT_L(0); PG8_BAR; PG8_MMA(1, 0, At, B0); PG8_MMA(1, 1, At, B1); PG8_BAR; PG8_SCHED;
.LBB0_354:
	s_add_u32 s2, s42, 0xfffc0080
	s_addc_u32 s76, s43, -1
	s_add_i32 s82, 0, 0x10000
	s_cmp_eq_u32 s88, 12
	s_cselect_b32 s91, s1, s76
	s_cselect_b32 s90, s34, s2
	s_cselect_b32 s77, s41, s78
	s_cselect_b32 s76, s69, s71
	s_add_i32 s2, 0, 0x14000
	v_add_u32_e32 v92, s82, v168
	v_add_u32_e32 v112, s2, v168
	ds_read_b128 v[80:83], v92
	ds_read_b128 v[84:87], v92 offset:1024
	ds_read_b128 v[88:91], v92 offset:2048
	ds_read_b128 v[92:95], v92 offset:3072
	ds_read_b128 v[160:163], v112
	ds_read_b128 v[164:167], v112 offset:1024
	ds_read_b128 v[172:175], v112 offset:2048
	ds_read_b128 v[176:179], v112 offset:3072
	s_add_i32 m0, s94, 0xc000
	ds_read_b128 v[180:183], v170
	ds_read_b128 v[184:187], v170 offset:1024
	ds_read_b128 v[192:195], v170 offset:2048
	ds_read_b128 v[196:199], v170 offset:3072
	ds_read_b128 v[200:203], v170 offset:4096
	ds_read_b128 v[204:207], v170 offset:5120
	ds_read_b128 v[208:211], v170 offset:6144
	ds_read_b128 v[212:215], v170 offset:7168
	global_load_lds_dwordx4 v156, s[42:43]
	s_add_i32 m0, s94, 0xe000
	s_nop 0
	global_load_lds_dwordx4 v158, s[42:43]
	s_cmp_lg_u32 s88, -2
	s_cbranch_scc1 .Lk0_wait
	s_cmp_gt_u32 s46, 1
	s_cbranch_scc1 .Lk0_skip
.Lk0_wait:
	s_waitcnt vmcnt(8)
.Lk0_skip:
	s_waitcnt lgkmcnt(0)
	s_barrier
	s_waitcnt lgkmcnt(0)
	v_mfma_f32_16x16x32_bf16 v[142:145], v[80:83], v[180:183], v[142:145]
	v_mfma_f32_16x16x32_bf16 v[138:141], v[88:91], v[180:183], v[138:141]
	v_mfma_f32_16x16x32_bf16 v[126:129], v[80:83], v[192:195], v[126:129]
	v_mfma_f32_16x16x32_bf16 v[122:125], v[88:91], v[192:195], v[122:125]
	v_mfma_f32_16x16x32_bf16 v[108:111], v[80:83], v[200:203], v[108:111]
	v_mfma_f32_16x16x32_bf16 v[104:107], v[88:91], v[200:203], v[104:107]
	v_mfma_f32_16x16x32_bf16 v[76:79], v[80:83], v[208:211], v[76:79]
	v_mfma_f32_16x16x32_bf16 v[72:75], v[88:91], v[208:211], v[72:75]
	v_mfma_f32_16x16x32_bf16 v[142:145], v[84:87], v[184:187], v[142:145]
	v_mfma_f32_16x16x32_bf16 v[138:141], v[92:95], v[184:187], v[138:141]
	v_mfma_f32_16x16x32_bf16 v[126:129], v[84:87], v[196:199], v[126:129]
	v_mfma_f32_16x16x32_bf16 v[122:125], v[92:95], v[196:199], v[122:125]
	v_mfma_f32_16x16x32_bf16 v[108:111], v[84:87], v[204:207], v[108:111]
	v_mfma_f32_16x16x32_bf16 v[104:107], v[92:95], v[204:207], v[104:107]
	v_mfma_f32_16x16x32_bf16 v[76:79], v[84:87], v[212:215], v[76:79]
	v_mfma_f32_16x16x32_bf16 v[72:75], v[92:95], v[212:215], v[72:75]
	v_mfma_f32_16x16x32_bf16 v[134:137], v[160:163], v[180:183], v[134:137]
	v_mfma_f32_16x16x32_bf16 v[130:133], v[172:175], v[180:183], v[130:133]
	v_mfma_f32_16x16x32_bf16 v[118:121], v[160:163], v[192:195], v[118:121]
	v_mfma_f32_16x16x32_bf16 v[114:117], v[172:175], v[192:195], v[114:117]
	v_mfma_f32_16x16x32_bf16 v[100:103], v[160:163], v[200:203], v[100:103]
	v_mfma_f32_16x16x32_bf16 v[96:99], v[172:175], v[200:203], v[96:99]
	v_mfma_f32_16x16x32_bf16 v[68:71], v[160:163], v[208:211], v[68:71]
	v_mfma_f32_16x16x32_bf16 v[64:67], v[172:175], v[208:211], v[64:67]
	v_mfma_f32_16x16x32_bf16 v[134:137], v[164:167], v[184:187], v[134:137]
	v_mfma_f32_16x16x32_bf16 v[130:133], v[176:179], v[184:187], v[130:133]
	v_mfma_f32_16x16x32_bf16 v[118:121], v[164:167], v[196:199], v[118:121]
	v_mfma_f32_16x16x32_bf16 v[114:117], v[176:179], v[196:199], v[114:117]
	v_mfma_f32_16x16x32_bf16 v[100:103], v[164:167], v[204:207], v[100:103]
	v_mfma_f32_16x16x32_bf16 v[96:99], v[176:179], v[204:207], v[96:99]
	v_mfma_f32_16x16x32_bf16 v[68:71], v[164:167], v[212:215], v[68:71]
	v_mfma_f32_16x16x32_bf16 v[64:67], v[176:179], v[212:215], v[64:67]
	s_barrier
	s_add_i32 s82, s82, s55
	s_mov_b32 m0, s82
	ds_read_b128 v[180:183], v170 offset:16384
	ds_read_b128 v[184:187], v170 offset:17408
	ds_read_b128 v[192:195], v170 offset:18432
	ds_read_b128 v[196:199], v170 offset:19456
	ds_read_b128 v[200:203], v170 offset:20480
	ds_read_b128 v[204:207], v170 offset:21504
	ds_read_b128 v[208:211], v170 offset:22528
	ds_read_b128 v[212:215], v170 offset:23552
	global_load_lds_dwordx4 v148, s[76:77]
	s_add_i32 m0, s82, 0x2000
	s_add_u32 vcc_lo, s76, 0x40000
	s_addc_u32 vcc_hi, s77, 0
	s_add_i32 s2, s2, s55
	global_load_lds_dwordx4 v152, s[76:77]
	s_mov_b32 m0, s2
	s_nop 0
	global_load_lds_dwordx4 v148, vcc
	s_add_i32 m0, s2, 0x2000
	s_nop 0
	global_load_lds_dwordx4 v152, vcc
	s_mov_b32 m0, s94
	s_nop 0
	global_load_lds_dwordx4 v146, s[90:91]
	s_mov_b32 m0, s95
	s_nop 0
	global_load_lds_dwordx4 v150, s[90:91]
	s_cmp_lg_u32 s88, -2
	s_cbranch_scc1 .Lk1_wait
	s_cmp_gt_u32 s46, 1
	s_cbranch_scc1 .Lk1_skip

; #define PG8_STAGE(bufoff, gbase, voff) do { _Pragma("unroll") for (int _i = 0; _i < 2; ++_i) \
;         __builtin_amdgcn_global_load_lds((const unsigned*)((const char*)(gbase) + (voff)[_i]), (PG8_LAS unsigned*)(lds + (bufoff) + ldsw + _i * 8192), 16, 0, 0); } while (0)
; #define PG8_LDA(dst, b, h) do { _Pragma("unroll") for (int m = 0; m < 4; ++m) _Pragma("unroll") for (int k = 0; k < 2; ++k) dst[m][k] = *(const PG8_LAS bf16x8*)(lds + PG8_SA(b, h) + aoff + m * 2048 + k * 1024); } while (0)
; #define PG8_LDB(dst, b, h) do { _Pragma("unroll") for (int n = 0; n < 2; ++n) _Pragma("unroll") for (int k = 0; k < 2; ++k) dst[n][k] = *(const PG8_LAS bf16x8*)(lds + PG8_SB(b, h) + boff + n * 2048 + k * 1024); } while (0)
; #define PG8_MMA(ai, bj, At, Bt) do { __builtin_amdgcn_s_setprio(1); _Pragma("unroll") for (int m = 0; m < 4; ++m) _Pragma("unroll") for (int n = 0; n < 2; ++n) _Pragma("unroll") for (int k = 0; k < 2; ++k) \
;         acc[ai][bj][m][n] = __builtin_amdgcn_mfma_f32_16x16x32_bf16(Bt[n][k], At[m][k], acc[ai][bj][m][n], 0, 0, 0); __builtin_amdgcn_s_setprio(0); } while (0)
; #define PG8_WAIT_V(n) asm volatile("s_waitcnt vmcnt(" #n ")" ::: "memory")
; #define PG8_WAIT_L(n) asm volatile("s_waitcnt lgkmcnt(" #n ")" ::: "memory")
; #define PG8_BAR __builtin_amdgcn_s_barrier()
; #define PG8_SCHED __builtin_amdgcn_sched_barrier(0)
; template <class Epi, class Sched, bool ALIGN_EPI = false, bool SP2 = false>
; __device__ __forceinline__ void gemm_phase(PG8_LAS unsigned char* lds, const Gemm g, const Sched& S, const Epi& E) {
;     ...
;             PG8_WAIT_V(8); PG8_WAIT_L(0); PG8_BAR; PG8_MMA(1, 0, At, B0); PG8_MMA(1, 1, At, B1); PG8_BAR; PG8_SCHED;
;             PG8_LDB(B0, 1, 0); PG8_LDB(B1, 1, 1); PG8_SCHED; PG8_LDA(At, 1, 0); PG8_STAGE(PG8_SA(0, 1), a2 + hstep, voffA);
;             PG8_WAIT_V(8); PG8_WAIT_L(0); PG8_BAR; PG8_MMA(0, 0, At, B0); PG8_MMA(0, 1, At, B1); PG8_BAR; PG8_SCHED;
.Lk1_skip:
	s_waitcnt lgkmcnt(0)
	s_barrier
	s_waitcnt lgkmcnt(0)
	v_mfma_f32_16x16x32_bf16 v[60:63], v[80:83], v[180:183], v[60:63]
	v_mfma_f32_16x16x32_bf16 v[56:59], v[88:91], v[180:183], v[56:59]
	v_mfma_f32_16x16x32_bf16 v[44:47], v[80:83], v[192:195], v[44:47]
	v_mfma_f32_16x16x32_bf16 v[40:43], v[88:91], v[192:195], v[40:43]
	v_mfma_f32_16x16x32_bf16 v[28:31], v[80:83], v[200:203], v[28:31]
	v_mfma_f32_16x16x32_bf16 v[24:27], v[88:91], v[200:203], v[24:27]
	v_mfma_f32_16x16x32_bf16 v[12:15], v[80:83], v[208:211], v[12:15]
	v_mfma_f32_16x16x32_bf16 v[8:11], v[88:91], v[208:211], v[8:11]
	v_mfma_f32_16x16x32_bf16 v[60:63], v[84:87], v[184:187], v[60:63]
	v_mfma_f32_16x16x32_bf16 v[56:59], v[92:95], v[184:187], v[56:59]
	v_mfma_f32_16x16x32_bf16 v[44:47], v[84:87], v[196:199], v[44:47]
	v_mfma_f32_16x16x32_bf16 v[40:43], v[92:95], v[196:199], v[40:43]
	v_mfma_f32_16x16x32_bf16 v[28:31], v[84:87], v[204:207], v[28:31]
	v_mfma_f32_16x16x32_bf16 v[24:27], v[92:95], v[204:207], v[24:27]
	v_mfma_f32_16x16x32_bf16 v[12:15], v[84:87], v[212:215], v[12:15]
	v_mfma_f32_16x16x32_bf16 v[8:11], v[92:95], v[212:215], v[8:11]
	v_mfma_f32_16x16x32_bf16 v[52:55], v[160:163], v[180:183], v[52:55]
	v_mfma_f32_16x16x32_bf16 v[48:51], v[172:175], v[180:183], v[48:51]
	v_mfma_f32_16x16x32_bf16 v[36:39], v[160:163], v[192:195], v[36:39]
	v_mfma_f32_16x16x32_bf16 v[32:35], v[172:175], v[192:195], v[32:35]
	v_mfma_f32_16x16x32_bf16 v[20:23], v[160:163], v[200:203], v[20:23]
	v_mfma_f32_16x16x32_bf16 v[16:19], v[172:175], v[200:203], v[16:19]
	v_mfma_f32_16x16x32_bf16 v[4:7], v[160:163], v[208:211], v[4:7]
	v_mfma_f32_16x16x32_bf16 v[0:3], v[172:175], v[208:211], v[0:3]
	v_mfma_f32_16x16x32_bf16 v[52:55], v[164:167], v[184:187], v[52:55]
	v_mfma_f32_16x16x32_bf16 v[48:51], v[176:179], v[184:187], v[48:51]
	v_mfma_f32_16x16x32_bf16 v[36:39], v[164:167], v[196:199], v[36:39]
	v_mfma_f32_16x16x32_bf16 v[32:35], v[176:179], v[196:199], v[32:35]
	v_mfma_f32_16x16x32_bf16 v[20:23], v[164:167], v[204:207], v[20:23]
	v_mfma_f32_16x16x32_bf16 v[16:19], v[176:179], v[204:207], v[16:19]
	v_mfma_f32_16x16x32_bf16 v[4:7], v[164:167], v[212:215], v[4:7]
	v_mfma_f32_16x16x32_bf16 v[0:3], v[176:179], v[212:215], v[0:3]
	s_barrier
	s_add_i32 s2, 0, 0x18000
	s_add_i32 s82, 0, 0x1c000
	v_add_u32_e32 v92, s2, v168
	v_add_u32_e32 v112, s82, v168
	ds_read_b128 v[80:83], v92
	ds_read_b128 v[84:87], v92 offset:1024
	ds_read_b128 v[88:91], v92 offset:2048
	ds_read_b128 v[92:95], v92 offset:3072
	ds_read_b128 v[160:163], v112
	ds_read_b128 v[164:167], v112 offset:1024
	ds_read_b128 v[172:175], v112 offset:2048
	ds_read_b128 v[176:179], v112 offset:3072
	s_add_u32 vcc_lo, s90, 0x40000
	s_addc_u32 vcc_hi, s91, 0
	s_mov_b32 m0, s96
	ds_read_b128 v[180:183], v170 offset:32768
	ds_read_b128 v[184:187], v170 offset:33792
	ds_read_b128 v[192:195], v170 offset:34816
	ds_read_b128 v[196:199], v170 offset:35840
	ds_read_b128 v[200:203], v170 offset:36864
	ds_read_b128 v[204:207], v170 offset:37888
	ds_read_b128 v[208:211], v170 offset:38912
	ds_read_b128 v[212:215], v170 offset:39936
	global_load_lds_dwordx4 v146, vcc
	s_mov_b32 m0, s97
	s_nop 0
	global_load_lds_dwordx4 v150, vcc
	s_waitcnt vmcnt(8)
	s_waitcnt lgkmcnt(0)
	s_barrier
	s_waitcnt lgkmcnt(0)
	v_mfma_f32_16x16x32_bf16 v[142:145], v[80:83], v[180:183], v[142:145]
	v_mfma_f32_16x16x32_bf16 v[138:141], v[88:91], v[180:183], v[138:141]
	v_mfma_f32_16x16x32_bf16 v[126:129], v[80:83], v[192:195], v[126:129]
	v_mfma_f32_16x16x32_bf16 v[122:125], v[88:91], v[192:195], v[122:125]
	v_mfma_f32_16x16x32_bf16 v[108:111], v[80:83], v[200:203], v[108:111]
	v_mfma_f32_16x16x32_bf16 v[104:107], v[88:91], v[200:203], v[104:107]
	v_mfma_f32_16x16x32_bf16 v[76:79], v[80:83], v[208:211], v[76:79]
	v_mfma_f32_16x16x32_bf16 v[72:75], v[88:91], v[208:211], v[72:75]
	v_mfma_f32_16x16x32_bf16 v[142:145], v[84:87], v[184:187], v[142:145]
	v_mfma_f32_16x16x32_bf16 v[138:141], v[92:95], v[184:187], v[138:141]
	v_mfma_f32_16x16x32_bf16 v[126:129], v[84:87], v[196:199], v[126:129]
	v_mfma_f32_16x16x32_bf16 v[122:125], v[92:95], v[196:199], v[122:125]
	v_mfma_f32_16x16x32_bf16 v[108:111], v[84:87], v[204:207], v[108:111]
	v_mfma_f32_16x16x32_bf16 v[104:107], v[92:95], v[204:207], v[104:107]
	v_mfma_f32_16x16x32_bf16 v[76:79], v[84:87], v[212:215], v[76:79]
	v_mfma_f32_16x16x32_bf16 v[72:75], v[92:95], v[212:215], v[72:75]
	v_mfma_f32_16x16x32_bf16 v[134:137], v[160:163], v[180:183], v[134:137]
	v_mfma_f32_16x16x32_bf16 v[130:133], v[172:175], v[180:183], v[130:133]
	v_mfma_f32_16x16x32_bf16 v[118:121], v[160:163], v[192:195], v[118:121]
	v_mfma_f32_16x16x32_bf16 v[114:117], v[172:175], v[192:195], v[114:117]
	v_mfma_f32_16x16x32_bf16 v[100:103], v[160:163], v[200:203], v[100:103]
	v_mfma_f32_16x16x32_bf16 v[96:99], v[172:175], v[200:203], v[96:99]
	v_mfma_f32_16x16x32_bf16 v[68:71], v[160:163], v[208:211], v[68:71]
	v_mfma_f32_16x16x32_bf16 v[64:67], v[172:175], v[208:211], v[64:67]
	v_mfma_f32_16x16x32_bf16 v[134:137], v[164:167], v[184:187], v[134:137]
	v_mfma_f32_16x16x32_bf16 v[130:133], v[176:179], v[184:187], v[130:133]
	v_mfma_f32_16x16x32_bf16 v[118:121], v[164:167], v[196:199], v[118:121]
	v_mfma_f32_16x16x32_bf16 v[114:117], v[176:179], v[196:199], v[114:117]
	v_mfma_f32_16x16x32_bf16 v[100:103], v[164:167], v[204:207], v[100:103]
	v_mfma_f32_16x16x32_bf16 v[96:99], v[176:179], v[204:207], v[96:99]
	v_mfma_f32_16x16x32_bf16 v[68:71], v[164:167], v[212:215], v[68:71]
	v_mfma_f32_16x16x32_bf16 v[64:67], v[176:179], v[212:215], v[64:67]
	s_barrier
; #define PG8_STAGE(bufoff, gbase, voff) do { _Pragma("unroll") for (int _i = 0; _i < 2; ++_i) \
;         __builtin_amdgcn_global_load_lds((const unsigned*)((const char*)(gbase) + (voff)[_i]), (PG8_LAS unsigned*)(lds + (bufoff) + ldsw + _i * 8192), 16, 0, 0); } while (0)
; #define PG8_LDA(dst, b, h) do { _Pragma("unroll") for (int m = 0; m < 4; ++m) _Pragma("unroll") for (int k = 0; k < 2; ++k) dst[m][k] = *(const PG8_LAS bf16x8*)(lds + PG8_SA(b, h) + aoff + m * 2048 + k * 1024); } while (0)
; #define PG8_MMA(ai, bj, At, Bt) do { __builtin_amdgcn_s_setprio(1); _Pragma("unroll") for (int m = 0; m < 4; ++m) _Pragma("unroll") for (int n = 0; n < 2; ++n) _Pragma("unroll") for (int k = 0; k < 2; ++k) \
;         acc[ai][bj][m][n] = __builtin_amdgcn_mfma_f32_16x16x32_bf16(Bt[n][k], At[m][k], acc[ai][bj][m][n], 0, 0, 0); __builtin_amdgcn_s_setprio(0); } while (0)
; #define PG8_WAIT_V(n) asm volatile("s_waitcnt vmcnt(" #n ")" ::: "memory")
; #define PG8_WAIT_L(n) asm volatile("s_waitcnt lgkmcnt(" #n ")" ::: "memory")
; #define PG8_BAR __builtin_amdgcn_s_barrier()
; #define PG8_SCHED __builtin_amdgcn_sched_barrier(0)
; template <class Epi, class Sched, bool ALIGN_EPI = false, bool SP2 = false>
; __device__ __forceinline__ void gemm_phase(PG8_LAS unsigned char* lds, const Gemm g, const Sched& S, const Epi& E) {
;     ...
;             PG8_LDA(At, 1, 1); PG8_STAGE(PG8_SB(1, 0), b3, voffB); PG8_STAGE(PG8_SB(1, 1), b3 + hstep, voffB); PG8_STAGE(PG8_SA(1, 0), a3, voffA);
;             PG8_WAIT_V(8); PG8_WAIT_L(0); PG8_BAR; PG8_MMA(1, 0, At, B0); PG8_MMA(1, 1, At, B1); PG8_BAR; PG8_SCHED;
;     ...
;         }
;         if constexpr (ALIGN_EPI) { if (wr == 0) PG8_BAR; }
	s_add_i32 s2, s2, s55
	s_add_i32 m0, s2, 0xffffff80
	ds_read_b128 v[180:183], v170 offset:49152
	ds_read_b128 v[184:187], v170 offset:50176
	ds_read_b128 v[192:195], v170 offset:51200
	ds_read_b128 v[196:199], v170 offset:52224
	ds_read_b128 v[200:203], v170 offset:53248
	ds_read_b128 v[204:207], v170 offset:54272
	ds_read_b128 v[208:211], v170 offset:55296
	ds_read_b128 v[212:215], v170 offset:56320
	global_load_lds_dwordx4 v148, s[76:77] offset:128
	s_add_i32 m0, s2, 0x1f80
	s_add_i32 s2, s82, s55
	global_load_lds_dwordx4 v152, s[76:77] offset:128
	s_add_u32 s76, s76, 0x40080
	s_addc_u32 s77, s77, 0
	s_mov_b32 m0, s2
	s_nop 0
	global_load_lds_dwordx4 v148, s[76:77]
	s_add_i32 m0, s2, 0x2000
	s_nop 0
	global_load_lds_dwordx4 v152, s[76:77]
	s_add_i32 m0, s62, 0xffffff80
	s_nop 0
	global_load_lds_dwordx4 v146, s[90:91] offset:128
	s_add_i32 m0, s63, 0xffffff80
	s_nop 0
	global_load_lds_dwordx4 v150, s[90:91] offset:128
	s_waitcnt vmcnt(8)
	s_waitcnt lgkmcnt(0)
	s_barrier
	s_waitcnt lgkmcnt(0)
	v_mfma_f32_16x16x32_bf16 v[60:63], v[80:83], v[180:183], v[60:63]
	v_mfma_f32_16x16x32_bf16 v[56:59], v[88:91], v[180:183], v[56:59]
	v_mfma_f32_16x16x32_bf16 v[44:47], v[80:83], v[192:195], v[44:47]
	v_mfma_f32_16x16x32_bf16 v[40:43], v[88:91], v[192:195], v[40:43]
	v_mfma_f32_16x16x32_bf16 v[28:31], v[80:83], v[200:203], v[28:31]
	v_mfma_f32_16x16x32_bf16 v[24:27], v[88:91], v[200:203], v[24:27]
	v_mfma_f32_16x16x32_bf16 v[12:15], v[80:83], v[208:211], v[12:15]
	v_mfma_f32_16x16x32_bf16 v[8:11], v[88:91], v[208:211], v[8:11]
	v_mfma_f32_16x16x32_bf16 v[60:63], v[84:87], v[184:187], v[60:63]
	v_mfma_f32_16x16x32_bf16 v[56:59], v[92:95], v[184:187], v[56:59]
	v_mfma_f32_16x16x32_bf16 v[44:47], v[84:87], v[196:199], v[44:47]
	v_mfma_f32_16x16x32_bf16 v[40:43], v[92:95], v[196:199], v[40:43]
	v_mfma_f32_16x16x32_bf16 v[28:31], v[84:87], v[204:207], v[28:31]
	v_mfma_f32_16x16x32_bf16 v[24:27], v[92:95], v[204:207], v[24:27]
	v_mfma_f32_16x16x32_bf16 v[12:15], v[84:87], v[212:215], v[12:15]
	v_mfma_f32_16x16x32_bf16 v[8:11], v[92:95], v[212:215], v[8:11]
	v_mfma_f32_16x16x32_bf16 v[52:55], v[160:163], v[180:183], v[52:55]
	v_mfma_f32_16x16x32_bf16 v[48:51], v[172:175], v[180:183], v[48:51]
	v_mfma_f32_16x16x32_bf16 v[36:39], v[160:163], v[192:195], v[36:39]
	v_mfma_f32_16x16x32_bf16 v[32:35], v[172:175], v[192:195], v[32:35]
	v_mfma_f32_16x16x32_bf16 v[20:23], v[160:163], v[200:203], v[20:23]
	v_mfma_f32_16x16x32_bf16 v[16:19], v[172:175], v[200:203], v[16:19]
	v_mfma_f32_16x16x32_bf16 v[4:7], v[160:163], v[208:211], v[4:7]
	v_mfma_f32_16x16x32_bf16 v[0:3], v[172:175], v[208:211], v[0:3]
	v_mfma_f32_16x16x32_bf16 v[52:55], v[164:167], v[184:187], v[52:55]
	v_mfma_f32_16x16x32_bf16 v[48:51], v[176:179], v[184:187], v[48:51]
	v_mfma_f32_16x16x32_bf16 v[36:39], v[164:167], v[196:199], v[36:39]
	v_mfma_f32_16x16x32_bf16 v[32:35], v[176:179], v[196:199], v[32:35]
	v_mfma_f32_16x16x32_bf16 v[20:23], v[164:167], v[204:207], v[20:23]
	v_mfma_f32_16x16x32_bf16 v[16:19], v[176:179], v[204:207], v[16:19]
	v_mfma_f32_16x16x32_bf16 v[4:7], v[164:167], v[212:215], v[4:7]
	v_mfma_f32_16x16x32_bf16 v[0:3], v[176:179], v[212:215], v[0:3]
	s_barrier
	s_add_i32 s88, s88, 2
	s_add_u32 s42, s42, 0x100
	s_addc_u32 s43, s43, 0
	s_add_u32 s71, s71, 0x100
	s_addc_u32 s78, s78, 0
	s_cmp_gt_u32 s88, 13
	s_cbranch_scc0 .LBB0_354
	s_and_b64 vcc, exec, s[66:67]
	s_cbranch_vccz .LBB0_357
	s_barrier
